# swa attention K/V loop: the loop-top wait no longer covers both in-flight register sets - each set is waited for (counted vmcnt) only right before its own LDS store
# baseline (speedup 1.0000x reference)
; template <int DQK>
; DI void attn_tile(const u16* __restrict__ q, int ldq, int qpos0, const Seg& s0, const Seg& s1, int nseg, bool has_sink,
;                   float sinkl2, u16* __restrict__ out, int ldo, char* lds) {
;     ...
;   const int tid = ltid & 255, wave = tid >> 6, lane = tid & 63, r = lane & 31, h = lane >> 5;
;   const int qi = wave * 32 + r;
;   bf16x8 qf[NKS];
; #pragma unroll
;   for (int ks = 0; ks < NKS; ++ks) qf[ks] = *(const bf16x8*)(q + (size_t)qi * ldq + ks * 16 + 8 * h);
;   const int nt0 = s0.n >> 6;
;   const int NT = nt0 + (nseg > 1 ? (s1.n >> 6) : 0);
;   uint4 kreg0, kreg1 = make_uint4(0, 0, 0, 0), vreg0;
;   uint4 krgB0, krgB1 = make_uint4(0, 0, 0, 0), vrgB0;
;   const int kkey0 = ltid / CPK, kpart0 = ltid % CPK;
;   const int kkey1 = (ltid + 512) / CPK, kpart1 = (ltid + 512) % CPK;
;   const bool k1 = (CPK == 12) && (ltid < 256);
;   const int vkey = ltid >> 3, vpart = ltid & 7;
;   typedef __attribute__((address_space(3))) const char* lds_cptr;
;   typedef short v4i16_t __attribute__((ext_vector_type(4)));
;   const lds_cptr vp0 = (lds_cptr)Vs + (4 * h + ((lane & 15) >> 2)) * (VST * 2) + ((lane >> 4) & 1) * 32 + (lane & 3) * 8;
;     ...
;   f32x16 o0 = zero16(), o1 = zero16();
;   float m = -1e30f, l = 0.f;
;     ...
;   ATT_LOADX(0, kreg0, kreg1, vreg0);
;   ATT_LOADX(1, krgB0, krgB1, vrgB0);
;   for (int i = 0; i < NT; i += 2) {
;     __syncthreads();
;     ATT_STOREX(kreg0, kreg1, vreg0);
;     __syncthreads();
;     if (i + 2 < NT) ATT_LOADX(i + 2, kreg0, kreg1, vreg0);
.LBB0_559:
	v_and_b32_e32 v3, 31, v2
	v_bfe_u32 v4, v2, 5, 1
	v_lshrrev_b32_e32 v5, 1, v2
	s_movk_i32 s20, 0x60
	s_waitcnt vmcnt(7)
	v_and_or_b32 v110, v5, s20, v3
	v_lshlrev_b32_e32 v100, 2, v4
	s_andn2_b64 vcc, exec, s[10:11]
	s_mov_b32 s10, 0
	s_cbranch_vccnz .LBB0_768
	v_readlane_b32 s24, v252, 20
	v_readlane_b32 s25, v252, 21
	s_lshl_b32 s22, s9, 6
	s_lshl_b64 s[20:21], s[24:25], 7
	s_add_u32 s11, s15, s20
	s_addc_u32 s15, s16, s21
	s_ashr_i32 s9, s8, 31
	s_lshl_b64 s[8:9], s[8:9], 12
	s_or_b32 s8, s8, s24
	s_mulk_i32 s9, 0x1600
	s_mul_hi_u32 s16, s8, 0x1600
	s_add_i32 s16, s16, s9
	s_mulk_i32 s8, 0x1600
	s_add_u32 s8, s50, s8
	s_addc_u32 s9, s51, s16
	s_lshl_b32 s16, s22, 1
	s_add_u32 s8, s8, s16
	v_lshlrev_b32_e32 v0, 7, v110
	s_addc_u32 s9, s9, 0
	v_lshl_add_u64 v[6:7], s[6:7], 0, v[0:1]
	v_lshlrev_b32_e32 v0, 4, v4
	s_add_u32 s8, s8, 0x300
	v_lshl_add_u64 v[4:5], v[6:7], 0, v[0:1]
	s_addc_u32 s9, s9, 0
	global_load_dwordx4 v[68:71], v[4:5], off
	global_load_dwordx4 v[72:75], v[4:5], off offset:32
	global_load_dwordx4 v[76:79], v[4:5], off offset:64
	global_load_dwordx4 v[80:83], v[4:5], off offset:96
	s_add_i32 s16, s14, 4
	v_ashrrev_i32_e32 v4, 31, v2
	s_sub_i32 s17, 64, s17
	v_lshrrev_b32_e32 v4, 29, v4
	s_cmp_gt_i32 s14, 1
	v_add_u32_e32 v4, v2, v4
	v_ashrrev_i32_e32 v105, 3, v2
	v_lshlrev_b32_e32 v11, 3, v2
	s_cselect_b32 s20, s9, s5
	s_cselect_b32 s21, s8, s4
	s_cselect_b32 s17, 64, s17
	v_ashrrev_i32_e32 v19, 3, v4
	v_and_b32_e32 v4, -8, v4
	v_and_b32_e32 v104, 56, v11
	v_mov_b32_e32 v6, s21
	v_mov_b32_e32 v7, s20
	v_add_u32_e32 v5, s17, v105
	v_sub_u32_e32 v10, v2, v4
	v_lshlrev_b32_e32 v4, 1, v104
	v_mad_i64_i32 v[6:7], s[20:21], v5, s87, v[6:7]
	v_mov_b32_e32 v5, v1
	v_lshl_add_u64 v[6:7], v[6:7], 0, v[4:5]
	global_load_dwordx4 v[88:91], v[6:7], off
	v_add_u32_e32 v6, s17, v19
	v_lshlrev_b32_e32 v102, 3, v10
	s_cselect_b32 s21, s15, s3
	s_cselect_b32 s20, s11, s2
	v_ashrrev_i32_e32 v7, 31, v6
	s_min_i32 s17, s14, 0
	v_ashrrev_i32_e32 v103, 31, v102
	v_lshlrev_b64 v[6:7], 7, v[6:7]
	s_lshl_b32 s17, s17, 6
	v_lshl_add_u64 v[6:7], s[20:21], 0, v[6:7]
	v_lshlrev_b64 v[8:9], 1, v[102:103]
	s_cmp_gt_i32 s14, 0
	v_lshl_add_u64 v[6:7], v[6:7], 0, v[8:9]
	s_cselect_b32 s20, s9, s5
	s_cselect_b32 s21, s8, s4
	global_load_dwordx4 v[84:87], v[6:7], off
	v_mov_b32_e32 v6, s21
	v_mov_b32_e32 v7, s20
	v_subrev_u32_e32 v12, s17, v105
	v_mad_i64_i32 v[6:7], s[20:21], v12, s87, v[6:7]
	v_lshl_add_u64 v[6:7], v[6:7], 0, v[4:5]
	global_load_dwordx4 v[96:99], v[6:7], off
	v_subrev_u32_e32 v6, s17, v19
	v_ashrrev_i32_e32 v7, 31, v6
	s_cselect_b32 s21, s15, s3
	s_cselect_b32 s20, s11, s2
	v_lshlrev_b64 v[6:7], 7, v[6:7]
	v_lshl_add_u64 v[6:7], s[20:21], 0, v[6:7]
	v_lshl_add_u64 v[6:7], v[6:7], 0, v[8:9]
	global_load_dwordx4 v[92:95], v[6:7], off
	v_mad_u32_u24 v109, v3, s60, v0
	v_and_b32_e32 v3, 64, v209
	v_xor_b32_e32 v107, 32, v209
	v_add_u32_e32 v108, 64, v3
	v_lshrrev_b32_e32 v5, 2, v2
	v_cmp_lt_i32_e32 vcc, v107, v108
	v_and_or_b32 v5, v5, 3, v100
	v_mul_u32_u24_e32 v5, 0xc0, v5
	v_cndmask_b32_e32 v3, v209, v107, vcc
	v_lshlrev_b32_e32 v2, 1, v2
	s_movk_i32 s20, 0xc0
	v_lshlrev_b32_e32 v111, 2, v3
	v_add_u32_e32 v3, s18, v100
	s_min_u32 s18, s18, 0x80
	v_and_or_b32 v2, v2, 32, v5
	v_and_b32_e32 v5, 24, v11
	v_lshlrev_b32_e32 v6, 4, v10
	v_mul_lo_u32 v7, v19, s60
	v_mul_lo_u32 v8, v105, s20
	v_add_u32_e32 v0, s19, v110
	v_subrev_u32_e32 v3, s18, v3
	v_mov_b32_e32 v18, 0
	s_mov_b32 s17, 1
	v_sub_u32_e32 v112, v3, v0
	v_mov_b32_e32 v116, 0xf149f2ca
	v_add_u32_e32 v113, v6, v7
	v_add_u32_e32 v114, v4, v8
	v_add_u32_e32 v115, v2, v5
	v_mov_b32_e32 v2, 0
	v_mov_b32_e32 v3, v18
	v_mov_b32_e32 v4, v18
	v_mov_b32_e32 v5, v18
	v_mov_b32_e32 v6, v18
	v_mov_b32_e32 v7, v18
	v_mov_b32_e32 v8, v18
	v_mov_b32_e32 v9, v18
	v_mov_b32_e32 v10, v18
	v_mov_b32_e32 v11, v18
	v_mov_b32_e32 v12, v18
	v_mov_b32_e32 v13, v18
	v_mov_b32_e32 v14, v18
	v_mov_b32_e32 v15, v18
	v_mov_b32_e32 v16, v18
	v_mov_b32_e32 v17, v18
	v_mov_b32_e32 v20, 0
	v_mov_b32_e32 v21, v18
	v_mov_b32_e32 v22, v18
	v_mov_b32_e32 v23, v18
	v_mov_b32_e32 v24, v18
	v_mov_b32_e32 v25, v18
	v_mov_b32_e32 v26, v18
	v_mov_b32_e32 v27, v18
	v_mov_b32_e32 v28, v18
	v_mov_b32_e32 v29, v18
	v_mov_b32_e32 v30, v18
	v_mov_b32_e32 v31, v18
	v_mov_b32_e32 v32, v18
	v_mov_b32_e32 v33, v18
	v_mov_b32_e32 v34, v18
	v_mov_b32_e32 v35, v18
	s_waitcnt vmcnt(0)
.LBB0_561:
	s_add_i32 s18, s17, 1
	s_cmp_ge_i32 s18, s16
	v_lshlrev_b32_e32 v0, 1, v104
	s_barrier
	s_waitcnt vmcnt(2)
	ds_write_b128 v113, v[92:95]
	ds_write_b128 v114, v[96:99] offset:9216
	s_waitcnt lgkmcnt(0)
	s_barrier
	s_cbranch_scc1 .Lswa_last
	s_cmp_lt_i32 s18, s14
	s_cselect_b64 s[18:19], -1, 0
	s_and_b64 s[20:21], s[18:19], exec
	s_cselect_b32 s22, 0, s14
	s_cselect_b32 s21, s15, s3
	s_cselect_b32 s20, s11, s2
	s_lshl_b32 s22, s22, 6
	s_sub_i32 s22, s10, s22
	v_add_u32_e32 v36, s22, v19
	v_add_u32_e32 v36, 0x80, v36
	v_ashrrev_i32_e32 v37, 31, v36
	v_lshlrev_b64 v[36:37], 7, v[36:37]
	v_lshl_add_u64 v[36:37], s[20:21], 0, v[36:37]
	s_and_b64 s[18:19], s[18:19], exec
	v_lshl_add_u64 v[36:37], v[102:103], 1, v[36:37]
	s_cselect_b32 s18, s9, s5
	s_cselect_b32 s19, s8, s4
	v_add_u32_e32 v38, s22, v105
	global_load_dwordx4 v[92:95], v[36:37], off
	v_mov_b32_e32 v36, s19
	v_mov_b32_e32 v37, s18
	v_add_u32_e32 v38, 0x80, v38
	v_mad_i64_i32 v[36:37], s[18:19], v38, s87, v[36:37]
	v_lshl_add_u64 v[36:37], v[36:37], 0, v[0:1]
	global_load_dwordx4 v[96:99], v[36:37], off

; template <int DQK>
; DI void attn_tile(const u16* __restrict__ q, int ldq, int qpos0, const Seg& s0, const Seg& s1, int nseg, bool has_sink,
;                   float sinkl2, u16* __restrict__ out, int ldo, char* lds) {
;     ...
;     float mx = sa[0];
; #pragma unroll
;     for (int g = 1; g < 16; ++g) mx = fmaxf(mx, sa[g]);
; #pragma unroll
;     for (int g = 0; g < 16; ++g) mx = fmaxf(mx, sb[g]);
;     mx = fmaxf(mx, __shfl_xor(mx, 32));
;     const float mn = fmaxf(m, mx);
;     const float alpha = __builtin_amdgcn_exp2f(m - mn);
;     m = mn;
;     float ps = 0.f;
; #pragma unroll
;     for (int g = 0; g < 16; ++g) { sa[g] = __builtin_amdgcn_exp2f(sa[g] - mn); ps += sa[g]; }
; #pragma unroll
;     for (int g = 0; g < 16; ++g) { sb[g] = __builtin_amdgcn_exp2f(sb[g] - mn); ps += sb[g]; }
;     l = l * alpha + ps;
; #pragma unroll
;     for (int g = 0; g < 16; ++g) { o0[g] *= alpha; o1[g] *= alpha; }
; #pragma unroll
;     for (int kt = 0; kt < 2; ++kt) {
; #pragma unroll
;       for (int s = 0; s < 2; ++s) {
;         const f32x16& sv = kt == 0 ? sa : sb;
;         uint4 pu;
;         pu.x = pack2(sv[8 * s + 0], sv[8 * s + 1]); pu.y = pack2(sv[8 * s + 2], sv[8 * s + 3]);
;         pu.z = pack2(sv[8 * s + 4], sv[8 * s + 5]); pu.w = pack2(sv[8 * s + 6], sv[8 * s + 7]);
;         bf16x8 pf = __builtin_bit_cast(bf16x8, pu);
;         const lds_cptr vp = vp0 + (kt * 32 + 16 * s) * (VST * 2);
;         {
;           s16x4 lo = ATT_VTR(vp);
;           s16x4 hi = ATT_VTR(vp + 8 * VST * 2);
;           bf16x8 vf = __builtin_shufflevector(lo, hi, 0, 1, 2, 3, 4, 5, 6, 7);
;           o0 = MFMA(vf, pf, o0);
;         }
;         {
;           s16x4 lo = ATT_VTR(vp + 64);
;           s16x4 hi = ATT_VTR(vp + 8 * VST * 2 + 64);
;           bf16x8 vf = __builtin_shufflevector(lo, hi, 0, 1, 2, 3, 4, 5, 6, 7);
;           o1 = MFMA(vf, pf, o1);
;         }
;       }
;     }
;   };
;   ATT_LOADX(0, kreg0, kreg1, vreg0);
;   ATT_LOADX(1, krgB0, krgB1, vrgB0);
;   for (int i = 0; i < NT; i += 2) {
;     __syncthreads();
;     ATT_STOREX(kreg0, kreg1, vreg0);
;     __syncthreads();
;     if (i + 2 < NT) ATT_LOADX(i + 2, kreg0, kreg1, vreg0);
;     compute(i);
;     __syncthreads();
;     ATT_STOREX(krgB0, krgB1, vrgB0);
;     __syncthreads();
;     if (i + 3 < NT) ATT_LOADX(i + 3, krgB0, krgB1, vrgB0);
.LBB0_565:
	s_nop 7
	v_max_f32_e32 v106, v53, v53
	v_max_f32_e32 v118, v52, v52
	v_max_f32_e32 v106, v118, v106
	v_max3_f32 v106, v106, v54, v55
	v_max3_f32 v106, v106, v56, v57
	v_max3_f32 v106, v106, v58, v59
	v_max3_f32 v106, v106, v60, v61
	v_max3_f32 v106, v106, v62, v63
	v_max3_f32 v106, v106, v64, v65
	v_max3_f32 v106, v106, v66, v67
	v_max3_f32 v106, v106, v36, v37
	v_max3_f32 v106, v106, v38, v39
	v_max3_f32 v106, v106, v40, v41
	v_max3_f32 v106, v106, v42, v43
	v_max3_f32 v106, v106, v44, v45
	v_max3_f32 v106, v106, v46, v47
	v_max3_f32 v106, v106, v48, v49
	v_max3_f32 v106, v106, v50, v51
	ds_bpermute_b32 v118, v111, v106
	s_add_i32 s18, s17, 2
	s_cmp_ge_i32 s18, s16
	s_waitcnt lgkmcnt(0)
	v_max3_f32 v118, v116, v106, v118
	v_sub_f32_e32 v36, v36, v118
	v_exp_f32_e32 v139, v36
	v_sub_f32_e32 v36, v37, v118
	v_exp_f32_e32 v140, v36
	v_sub_f32_e32 v36, v38, v118
	v_exp_f32_e32 v141, v36
	v_sub_f32_e32 v36, v39, v118
	v_sub_f32_e32 v52, v52, v118
	v_exp_f32_e32 v142, v36
	v_sub_f32_e32 v36, v40, v118
	v_sub_f32_e32 v106, v116, v118
	v_exp_f32_e32 v116, v52
	v_sub_f32_e32 v52, v53, v118
	v_exp_f32_e32 v143, v36
	v_sub_f32_e32 v36, v41, v118
	v_exp_f32_e32 v121, v52
	v_sub_f32_e32 v52, v54, v118
	v_exp_f32_e32 v144, v36
	v_sub_f32_e32 v36, v42, v118
	v_exp_f32_e32 v123, v52
	v_sub_f32_e32 v52, v55, v118
	v_exp_f32_e32 v145, v36
	v_sub_f32_e32 v36, v43, v118
	v_exp_f32_e32 v125, v52
	v_sub_f32_e32 v52, v56, v118
	v_exp_f32_e32 v146, v36
	v_sub_f32_e32 v36, v44, v118
	v_exp_f32_e32 v127, v52
	v_sub_f32_e32 v52, v57, v118
	v_exp_f32_e32 v147, v36
	v_sub_f32_e32 v36, v45, v118
	v_exp_f32_e32 v128, v52
	v_sub_f32_e32 v52, v58, v118
	v_exp_f32_e32 v148, v36
	v_sub_f32_e32 v36, v46, v118
	v_exp_f32_e32 v129, v52
	v_sub_f32_e32 v52, v59, v118
	v_exp_f32_e32 v149, v36
	v_sub_f32_e32 v36, v47, v118
	v_exp_f32_e32 v130, v52
	v_exp_f32_e32 v119, v36
	v_sub_f32_e32 v36, v48, v118
	v_exp_f32_e32 v106, v106
	ds_read_b64_tr_b16 v[40:41], v115 offset:9216
	ds_read_b64_tr_b16 v[42:43], v115 offset:10752
	v_exp_f32_e32 v122, v36
	v_sub_f32_e32 v36, v49, v118
	v_sub_f32_e32 v52, v60, v118
	v_exp_f32_e32 v124, v36
	v_sub_f32_e32 v36, v50, v118
	v_exp_f32_e32 v131, v52
	v_sub_f32_e32 v52, v61, v118
	v_exp_f32_e32 v126, v36
	v_sub_f32_e32 v36, v51, v118
	v_exp_f32_e32 v132, v52
	v_sub_f32_e32 v52, v62, v118
	v_exp_f32_e32 v120, v36
	v_pk_mul_f32 v[34:35], v[34:35], v[106:107] op_sel_hi:[1,0]
	v_pk_mul_f32 v[32:33], v[32:33], v[106:107] op_sel_hi:[1,0]
	v_pk_mul_f32 v[30:31], v[30:31], v[106:107] op_sel_hi:[1,0]
	v_pk_mul_f32 v[28:29], v[28:29], v[106:107] op_sel_hi:[1,0]
	v_pk_mul_f32 v[26:27], v[26:27], v[106:107] op_sel_hi:[1,0]
	v_pk_mul_f32 v[24:25], v[24:25], v[106:107] op_sel_hi:[1,0]
	v_pk_mul_f32 v[22:23], v[22:23], v[106:107] op_sel_hi:[1,0]
	v_pk_mul_f32 v[20:21], v[20:21], v[106:107] op_sel_hi:[1,0]
	v_cvt_pk_bf16_f32 v36, v116, v121
	v_cvt_pk_bf16_f32 v37, v123, v125
	v_cvt_pk_bf16_f32 v38, v127, v128
	v_cvt_pk_bf16_f32 v39, v129, v130
	v_exp_f32_e32 v133, v52
	v_sub_f32_e32 v52, v63, v118
	s_waitcnt lgkmcnt(0)
	v_mfma_f32_32x32x16_bf16 v[20:35], v[40:43], v[36:39], v[20:35]
	ds_read_b64_tr_b16 v[40:41], v115 offset:9280
	ds_read_b64_tr_b16 v[42:43], v115 offset:10816
	v_exp_f32_e32 v134, v52
	v_sub_f32_e32 v52, v64, v118
	v_exp_f32_e32 v135, v52
	v_sub_f32_e32 v52, v65, v118
	v_exp_f32_e32 v136, v52
	v_sub_f32_e32 v52, v66, v118
	v_exp_f32_e32 v137, v52
	v_sub_f32_e32 v52, v67, v118
	v_pk_mul_f32 v[16:17], v[16:17], v[106:107] op_sel_hi:[1,0]
	v_pk_mul_f32 v[14:15], v[14:15], v[106:107] op_sel_hi:[1,0]
	v_pk_mul_f32 v[12:13], v[12:13], v[106:107] op_sel_hi:[1,0]
	v_pk_mul_f32 v[10:11], v[10:11], v[106:107] op_sel_hi:[1,0]
	v_pk_mul_f32 v[8:9], v[8:9], v[106:107] op_sel_hi:[1,0]
	v_pk_mul_f32 v[6:7], v[6:7], v[106:107] op_sel_hi:[1,0]
	v_pk_mul_f32 v[4:5], v[4:5], v[106:107] op_sel_hi:[1,0]
	v_pk_mul_f32 v[2:3], v[2:3], v[106:107] op_sel_hi:[1,0]
	v_exp_f32_e32 v138, v52
	s_waitcnt lgkmcnt(0)
	v_mfma_f32_32x32x16_bf16 v[2:17], v[40:43], v[36:39], v[2:17]
	ds_read_b64_tr_b16 v[40:41], v115 offset:12288
	ds_read_b64_tr_b16 v[42:43], v115 offset:13824
	v_cvt_pk_bf16_f32 v36, v131, v132
	v_cvt_pk_bf16_f32 v37, v133, v134
	v_cvt_pk_bf16_f32 v38, v135, v136
	v_cvt_pk_bf16_f32 v39, v137, v138
	s_waitcnt lgkmcnt(0)
	s_nop 0
	v_mfma_f32_32x32x16_bf16 v[20:35], v[40:43], v[36:39], v[20:35]
	ds_read_b64_tr_b16 v[40:41], v115 offset:12352
	ds_read_b64_tr_b16 v[42:43], v115 offset:13888
	s_waitcnt lgkmcnt(0)
	v_mfma_f32_32x32x16_bf16 v[2:17], v[40:43], v[36:39], v[2:17]
	ds_read_b64_tr_b16 v[40:41], v115 offset:15360
	ds_read_b64_tr_b16 v[42:43], v115 offset:16896
	v_cvt_pk_bf16_f32 v36, v139, v140
	v_cvt_pk_bf16_f32 v37, v141, v142
	v_cvt_pk_bf16_f32 v38, v143, v144
	v_cvt_pk_bf16_f32 v39, v145, v146
	s_waitcnt lgkmcnt(0)
	s_nop 0
	v_mfma_f32_32x32x16_bf16 v[20:35], v[40:43], v[36:39], v[20:35]
	ds_read_b64_tr_b16 v[40:41], v115 offset:15424
	ds_read_b64_tr_b16 v[42:43], v115 offset:16960
	s_waitcnt lgkmcnt(0)
	v_mfma_f32_32x32x16_bf16 v[2:17], v[40:43], v[36:39], v[2:17]
	ds_read_b64_tr_b16 v[40:41], v115 offset:18432
	ds_read_b64_tr_b16 v[42:43], v115 offset:19968
	v_cvt_pk_bf16_f32 v36, v147, v148
	v_cvt_pk_bf16_f32 v37, v149, v119
	v_cvt_pk_bf16_f32 v38, v122, v124
	v_cvt_pk_bf16_f32 v39, v126, v120
	s_waitcnt lgkmcnt(0)
	s_nop 0
	v_mfma_f32_32x32x16_bf16 v[20:35], v[40:43], v[36:39], v[20:35]
	ds_read_b64_tr_b16 v[40:41], v115 offset:18496
	ds_read_b64_tr_b16 v[42:43], v115 offset:20032
	s_waitcnt lgkmcnt(0)
	s_barrier
	s_waitcnt vmcnt(2)
	ds_write_b128 v113, v[84:87]
	ds_write_b128 v114, v[88:91] offset:9216
	s_waitcnt lgkmcnt(0)
	s_barrier
	v_mfma_f32_32x32x16_bf16 v[2:17], v[40:43], v[36:39], v[2:17]
	s_cbranch_scc1 .LBB0_567
	s_cmp_lt_i32 s18, s14
	s_cselect_b64 s[20:21], -1, 0
	s_and_b64 s[22:23], s[20:21], exec
	s_cselect_b32 s19, 0, s14
	s_cselect_b32 s23, s15, s3
	s_cselect_b32 s22, s11, s2
	s_lshl_b32 s19, s19, 6
	s_sub_i32 s19, s10, s19
	v_add_u32_e32 v36, s19, v19
	v_add_u32_e32 v36, 0xc0, v36
	v_ashrrev_i32_e32 v37, 31, v36
	v_lshlrev_b64 v[36:37], 7, v[36:37]
	v_lshl_add_u64 v[36:37], s[22:23], 0, v[36:37]
	s_and_b64 s[20:21], s[20:21], exec
	v_lshl_add_u64 v[36:37], v[102:103], 1, v[36:37]
	s_cselect_b32 s20, s9, s5
	s_cselect_b32 s21, s8, s4
	v_add_u32_e32 v38, s19, v105
	global_load_dwordx4 v[84:87], v[36:37], off
	v_mov_b32_e32 v36, s21
	v_mov_b32_e32 v37, s20
	v_add_u32_e32 v38, 0xc0, v38
	v_mad_i64_i32 v[36:37], s[20:21], v38, s87, v[36:37]
	v_lshl_add_u64 v[36:37], v[36:37], 0, v[0:1]
	global_load_dwordx4 v[88:91], v[36:37], off

; template <int DQK>
; DI void attn_tile(const u16* __restrict__ q, int ldq, int qpos0, const Seg& s0, const Seg& s1, int nseg, bool has_sink,
;                   float sinkl2, u16* __restrict__ out, int ldo, char* lds) {
;     ...
;   for (int i = 0; i < NT; i += 2) {
;     __syncthreads();
;     ATT_STOREX(kreg0, kreg1, vreg0);
;     __syncthreads();
;     if (i + 2 < NT) ATT_LOADX(i + 2, kreg0, kreg1, vreg0);
;     compute(i);
;     __syncthreads();
;     ATT_STOREX(krgB0, krgB1, vrgB0);
;     __syncthreads();
;     if (i + 3 < NT) ATT_LOADX(i + 3, krgB0, krgB1, vrgB0);
;     compute(i + 1);
.Lswa_last:
	s_waitcnt vmcnt(0)
	s_branch .LBB0_563
